# adds: GLA scan v chunk tile also staged HBM->LDS by LDS-DMA (4 per wave, +8 KiB static LDS) and read with ds_read_b32, replacing 16 dword buffer loads per thread per step
# baseline (speedup 1.0000x reference)
; __device__ __forceinline__ void gla_scan_phase2(LAS unsigned char* lds, const bf16_t* proj, const float* gbuf, const float* wgu  , const float* bg  ,
;                                                 bf16_t* ob0, bf16_t* ob1) {
;     ...
;         if (wave < 4) {
;             const int d = tid & 127, seg = (tid >> 7) & 1;
;             const int zd = wave;
;             bf16x8 wbh, wbl;
;             {
;                 unsigned hi_[4], lo_[4];
; #pragma unroll
;                 for (int q = 0; q < 4; ++q) {
;                     const float w0 = wgu[(size_t)(dir * 16 + 8 * hh + 2 * q) * 512 + h * 128 + 32 * zd + r], w1 = wgu[(size_t)(dir * 16 + 8 * hh + 2 * q + 1) * 512 + h * 128 + 32 * zd + r];
;                     hi_[q] = pk2(w0, w1); lo_[q] = pk2(w0 - bflo(hi_[q]), w1 - bfhi(hi_[q]));
;                 }
;                 wbh = __builtin_bit_cast(bf16x8, (u32x4){hi_[0], hi_[1], hi_[2], hi_[3]}); wbl = __builtin_bit_cast(bf16x8, (u32x4){lo_[0], lo_[1], lo_[2], lo_[3]});
;             }
;             const float zbias = bg[dir * 512 + h * 128 + 32 * zd + r];
;             const __amdgpu_buffer_rsrc_t prs = __builtin_amdgcn_make_buffer_rsrc((void*)proj, 0, (unsigned)((size_t)MTOK * GINP * 2), 0x00020000);
;             const unsigned qvoff = (unsigned)((16 * seg * GINP + h * 128 + d) * 2), vvoff = (unsigned)((16 * seg * GINP + 1024 + h * 256 + 2 * d) * 2);
;             f32x4 gna, gnb;
;             { const float* grow = gbuf + (size_t)(b * SEQ + (dir ? NCH - 1 : 0) * CH + r) * 32 + dir * 16 + 8 * hh; gna = *(const f32x4*)grow; gnb = *(const f32x4*)(grow + 4); }
;             for (int n = 0; n <= NCH; ++n) {
;                 if (n < NCH) {
;                     const int tok0 = b * SEQ + (dir ? NCH - 1 - n : n) * CH;
;                     LAS unsigned char* set = lds + (n & 1) * G2_SET;
;                     const f32x4 ga = gna, gb = gnb;
;                     const unsigned srow = (unsigned)tok0 * (unsigned)(GINP * 2);
;                     unsigned short qv[16], kv[16];
; #pragma unroll
;                     for (int ii = 0; ii < 16; ++ii) { qv[ii] = __builtin_amdgcn_raw_buffer_load_b16(prs, qvoff, srow + (unsigned)(ii * GINP * 2), 0);
;                                                        kv[ii] = __builtin_amdgcn_raw_buffer_load_b16(prs, qvoff + 1024u, srow + (unsigned)(ii * GINP * 2), 0); }
;                     unsigned vw[16];
; #pragma unroll
.LBB0_217:
	s_and_b64 vcc, exec, s[6:7]
	s_cbranch_vccz .LBB0_212
	s_nop 7
	v_lshl_or_b32 v0, s8, 13, v198
	s_lshl_b32 s0, s15, 7
	v_or_b32_e32 v0, s0, v0
	v_lshlrev_b32_e32 v160, 2, v0
	v_lshl_add_u64 v[0:1], s[16:17], 0, v[160:161]
	v_lshl_add_u64 v[0:1], s[22:23], 2, v[0:1]
	v_mov_b32_e32 v193, v161
	v_lshl_add_u64 v[0:1], v[0:1], 0, v[192:193]
	global_load_dword v2, v[0:1], off
	global_load_dword v3, v[0:1], off offset:2048
	s_movk_i32 s6, 0x1000
	s_lshl_b32 s9, s9, 11
	v_lshlrev_b32_e32 v160, 2, v188
	s_mov_b32 s20, 0
	v_or_b32_e32 v52, s9, v186
	s_waitcnt vmcnt(0)
	v_cvt_pk_bf16_f32 v32, v2, v3
	v_lshlrev_b32_e32 v4, 16, v32
	v_and_b32_e32 v5, 0xffff0000, v32
	v_pk_add_f32 v[2:3], v[2:3], v[4:5] neg_lo:[0,1] neg_hi:[0,1]
	s_nop 0
	v_cvt_pk_bf16_f32 v36, v2, v3
	v_add_co_u32_e32 v2, vcc, s6, v0
	s_movk_i32 s6, 0x2000
	s_nop 0
	v_addc_co_u32_e32 v3, vcc, 0, v1, vcc
	v_add_co_u32_e32 v4, vcc, s6, v0
	s_movk_i32 s6, 0x3000
	s_nop 0
	v_addc_co_u32_e32 v5, vcc, 0, v1, vcc
	global_load_dword v6, v[4:5], off offset:-4096
	global_load_dword v7, v[2:3], off offset:2048
	v_add_co_u32_e32 v0, vcc, s6, v0
	s_lshl_b32 s6, s8, 9
	s_nop 0
	v_addc_co_u32_e32 v1, vcc, 0, v1, vcc
	s_or_b32 s6, s0, s6
	s_cmp_lg_u32 s8, 0
	s_cselect_b64 s[68:69], -1, 0
	s_cmp_eq_u32 s8, 0
	s_cselect_b64 s[48:49], -1, 0
	s_waitcnt vmcnt(0)
	v_cvt_pk_bf16_f32 v33, v6, v7
	v_lshlrev_b32_e32 v2, 16, v33
	v_and_b32_e32 v3, 0xffff0000, v33
	v_pk_add_f32 v[2:3], v[6:7], v[2:3] neg_lo:[0,1] neg_hi:[0,1]
	s_nop 0
	v_cvt_pk_bf16_f32 v37, v2, v3
	global_load_dword v2, v[4:5], off
	global_load_dword v3, v[4:5], off offset:2048
	s_waitcnt vmcnt(0)
	v_cvt_pk_bf16_f32 v34, v2, v3
	v_lshlrev_b32_e32 v4, 16, v34
	v_and_b32_e32 v5, 0xffff0000, v34
	v_pk_add_f32 v[2:3], v[2:3], v[4:5] neg_lo:[0,1] neg_hi:[0,1]
	s_nop 0
	v_cvt_pk_bf16_f32 v38, v2, v3
	global_load_dword v2, v[0:1], off
	global_load_dword v3, v[0:1], off offset:2048
	s_waitcnt vmcnt(0)
	v_cvt_pk_bf16_f32 v35, v2, v3
	v_lshlrev_b32_e32 v0, 16, v35
	v_and_b32_e32 v1, 0xffff0000, v35
	v_pk_add_f32 v[0:1], v[2:3], v[0:1] neg_lo:[0,1] neg_hi:[0,1]
	s_nop 0
	v_cvt_pk_bf16_f32 v39, v0, v1
	v_add_u32_e32 v0, s6, v199
	v_ashrrev_i32_e32 v1, 31, v0
	v_lshl_add_u64 v[0:1], v[0:1], 2, s[18:19]
	global_load_dword v0, v[0:1], off
	v_or_b32_e32 v1, s0, v200
	s_and_b64 s[6:7], s[48:49], exec
	v_lshlrev_b32_e32 v50, 1, v1
	v_lshl_or_b32 v1, s15, 9, v213
	s_cselect_b32 s0, 0, 0x7e0
	v_or_b32_e32 v51, 0x800, v1
	v_or_b32_e32 v1, s0, v186
	v_or_b32_e32 v2, s9, v1
	v_ashrrev_i32_e32 v3, 31, v2
	v_readlane_b32 s6, v253, 19
	v_lshlrev_b64 v[2:3], 7, v[2:3]
	v_readlane_b32 s7, v253, 20
	s_lshl_b32 s28, s8, 6
	v_lshl_add_u64 v[48:49], v[190:191], 0, s[28:29]
	v_lshl_add_u64 v[2:3], s[6:7], 0, v[2:3]
	v_lshl_add_u64 v[2:3], v[2:3], 0, s[28:29]
	v_lshl_add_u64 v[2:3], v[2:3], 0, v[160:161]
	global_load_dwordx4 v[40:43], v[2:3], off offset:16
	global_load_dwordx4 v[44:47], v[2:3], off
	v_or_b32_e32 v53, 0x400, v50
	s_xor_b64 s[50:51], s[40:41], s[48:49]
	s_xor_b64 s[52:53], s[42:43], s[48:49]
	s_xor_b64 s[54:55], s[44:45], s[48:49]
	s_xor_b64 s[56:57], s[46:47], s[48:49]
	s_mov_b32 s8, 63
	s_waitcnt vmcnt(2)
	v_mov_b32_e32 v1, v0
	v_mov_b32_e32 v2, v0
	v_mov_b32_e32 v3, v0
	v_mov_b32_e32 v4, v0
	v_mov_b32_e32 v5, v0
	v_mov_b32_e32 v6, v0
	v_mov_b32_e32 v7, v0
	v_mov_b32_e32 v8, v0
	v_mov_b32_e32 v9, v0
	v_mov_b32_e32 v10, v0
	v_mov_b32_e32 v11, v0
	v_mov_b32_e32 v12, v0
	v_mov_b32_e32 v13, v0
	v_mov_b32_e32 v14, v0
	v_mov_b32_e32 v15, v0
	v_lshrrev_b32_e32 v171, 6, v179
	v_bfe_u32 v176, v179, 5, 1
	v_lshl_add_u32 v176, v171, 3, v176
	v_mul_u32_u24_e32 v176, 0x1a00, v176
	v_and_b32_e32 v177, 31, v179
	v_lshlrev_b32_e32 v177, 4, v177
	v_add_u32_e32 v176, v176, v177
	s_lshl_b32 s0, s15, 9
	s_addk_i32 s0, 0x800
	v_add_u32_e32 v176, s0, v176
	v_lshlrev_b32_e32 v177, 12, v171
	v_mov_b32_e32 v170, 0x22000
	v_mov_b32_e32 v175, 0x1f600
	v_cmp_gt_u32_e32 vcc, 2, v171
	s_nop 1
	v_cndmask_b32_e32 v170, v170, v175, vcc
	v_add_u32_e32 v177, v177, v170
	v_bfe_u32 v170, v179, 7, 1
	v_mul_u32_u24_e32 v170, 0x4a00, v170
	v_and_b32_e32 v175, 0x7f, v179
	v_lshl_add_u32 v170, v175, 2, v170
	v_add_u32_e32 v170, 0x1f600, v170
	v_and_b32_e32 v172, 15, v179
	v_lshlrev_b32_e32 v172, 4, v172
	v_bfe_u32 v174, v179, 4, 2
	v_lshrrev_b32_e32 v173, 6, v179
	v_lshl_add_u32 v174, v173, 3, v174
	v_mul_u32_u24_e32 v174, 0x1a00, v174
	v_add_u32_e32 v172, v172, v174
	s_lshl_b32 s0, s15, 8
	v_add_u32_e32 v172, s0, v172
	v_lshlrev_b32_e32 v174, 11, v173
	v_add_u32_e32 v174, 0x1b600, v174
	v_and_b32_e32 v173, 0x7f, v179
	v_lshlrev_b32_e32 v173, 1, v173
	v_bfe_u32 v175, v179, 7, 1
	v_lshl_add_u32 v173, v175, 12, v173
	v_add_u32_e32 v173, 0x1b600, v173
	s_and_b64 s[6:7], s[48:49], exec
	s_cselect_b32 s0, s20, s8
	s_lshl_b32 s0, s0, 5
	s_add_i32 s0, s0, s9
	s_mulk_i32 s0, 0x1a00
	v_readfirstlane_b32 s26, v174
	s_add_u32 s78, s64, s0
	s_addc_u32 s79, s65, 0
	s_add_u32 s80, s78, 0x6800
	s_addc_u32 s81, s79, 0
	s_add_u32 s82, s78, 0x400
	s_addc_u32 s83, s79, 0
	s_add_u32 s24, s80, 0x400
	s_addc_u32 s25, s81, 0
	s_mov_b32 m0, s26
	s_nop 0
	global_load_lds_dwordx4 v172, s[78:79]
	s_add_i32 m0, s26, 0x400
	s_nop 0
	global_load_lds_dwordx4 v172, s[80:81]
	s_add_i32 m0, s26, 0x2000
	s_nop 0
	global_load_lds_dwordx4 v172, s[82:83]
	s_add_i32 m0, s26, 0x2400
	s_nop 0
	global_load_lds_dwordx4 v172, s[24:25]
	v_readfirstlane_b32 s33, v177
	s_nop 3
	s_mov_b32 m0, s33
	s_nop 0
	global_load_lds_dwordx4 v176, s[78:79]
	s_add_u32 s6, s78, 0x3400
	s_addc_u32 s7, s79, 0
	s_add_i32 m0, s33, 0x400
	s_nop 0
	global_load_lds_dwordx4 v176, s[6:7]
	s_add_i32 m0, s33, 0x800
	s_nop 0
	global_load_lds_dwordx4 v176, s[80:81]
	s_add_u32 s6, s80, 0x3400
	s_addc_u32 s7, s81, 0
	s_add_i32 m0, s33, 0xc00
	s_nop 0
	global_load_lds_dwordx4 v176, s[6:7]
	s_branch .LBB0_220
; #define LAS __attribute__((address_space(3)))
; #define G2_BAR() do { asm volatile("s_waitcnt lgkmcnt(0)" ::: "memory"); __builtin_amdgcn_s_barrier(); asm volatile("" ::: "memory"); } while (0)
; __device__ __forceinline__ void gla_scan_phase2(LAS unsigned char* lds, const bf16_t* proj, const float* gbuf, const float* wgu  , const float* bg  ,
;                                                 bf16_t* ob0, bf16_t* ob1) {
;     ...
;                         unsigned c0[8], c1[8];
; #pragma unroll
;                         for (int t = 0; t < 8; ++t) { const unsigned a_ = vw[2 * t], b_ = vw[2 * t + 1]; c0[t] = (a_ & 0xffffu) | (b_ << 16); c1[t] = (a_ >> 16) | (b_ & 0xffff0000u); }
;                         *(LAS u32x4*)(set + G2_VT + (2 * d) * 80 + seg * 32) = (u32x4){c0[0], c0[1], c0[2], c0[3]};
;                         *(LAS u32x4*)(set + G2_VT + (2 * d) * 80 + seg * 32 + 16) = (u32x4){c0[4], c0[5], c0[6], c0[7]};
;                         *(LAS u32x4*)(set + G2_VT + (2 * d + 1) * 80 + seg * 32) = (u32x4){c1[0], c1[1], c1[2], c1[3]};
;                         *(LAS u32x4*)(set + G2_VT + (2 * d + 1) * 80 + seg * 32 + 16) = (u32x4){c1[4], c1[5], c1[6], c1[7]};
;                     }
;                     G2_BAR();
.LBB0_219:
	s_or_b64 exec, exec, s[6:7]
	s_nop 0
	v_lshrrev_b32_e32 v17, 16, v68
	s_nop 0
	v_lshrrev_b32_e32 v18, 16, v66
	s_nop 0
	v_lshrrev_b32_e32 v19, 16, v64
	v_and_b32_e32 v16, 0xffff, v68
	v_and_or_b32 v20, v69, s77, v17
	v_and_b32_e32 v17, 0xffff, v66
	v_and_or_b32 v21, v67, s77, v18
	v_and_b32_e32 v18, 0xffff, v64
	s_nop 0
	v_and_or_b32 v22, v65, s77, v19
	s_nop 0
	v_and_b32_e32 v19, 0xffff, v62
	s_nop 0
	v_lshrrev_b32_e32 v25, 16, v60
	s_nop 0
	v_lshrrev_b32_e32 v26, 16, v58
	s_nop 0
	v_lshrrev_b32_e32 v27, 16, v56
	v_lshl_or_b32 v16, v69, 16, v16
	v_lshl_or_b32 v17, v67, 16, v17
	v_lshl_or_b32 v18, v65, 16, v18
	v_lshl_or_b32 v19, v63, 16, v19
	v_lshrrev_b32_e32 v23, 16, v62
	v_and_b32_e32 v24, 0xffff, v60
	v_and_or_b32 v28, v61, s77, v25
	v_and_b32_e32 v25, 0xffff, v58
	v_and_or_b32 v29, v59, s77, v26
	v_and_b32_e32 v26, 0xffff, v56
	s_nop 0
	v_and_or_b32 v30, v57, s77, v27
	s_nop 0
	v_and_b32_e32 v27, 0xffff, v54
	v_lshrrev_b32_e32 v31, 16, v54
	v_add3_u32 v54, s15, v205, v204
	v_and_or_b32 v23, v63, s77, v23
	v_lshl_or_b32 v24, v61, 16, v24
	v_lshl_or_b32 v25, v59, 16, v25
	v_lshl_or_b32 v26, v57, 16, v26
	s_nop 0
	v_lshl_or_b32 v27, v55, 16, v27
	v_and_or_b32 v31, v55, s77, v31
	ds_write_b128 v54, v[16:19] offset:18944
	ds_write_b128 v54, v[24:27] offset:18960
	ds_write_b128 v54, v[20:23] offset:19024
	ds_write_b128 v54, v[28:31] offset:19040
	s_waitcnt lgkmcnt(0)
	s_barrier
	s_cmp_eq_u32 s20, 63
	s_cbranch_scc1 .Lg2dma_skip
	s_and_b64 s[6:7], s[48:49], exec
	s_cselect_b32 s0, s20, s8
	s_cselect_b32 s6, 1, -1
	s_add_i32 s0, s0, s6
	s_lshl_b32 s0, s0, 5
	s_add_i32 s0, s0, s9
	s_mulk_i32 s0, 0x1a00
	v_readfirstlane_b32 s26, v174
	s_add_u32 s78, s64, s0
	s_addc_u32 s79, s65, 0
	s_add_u32 s80, s78, 0x6800
	s_addc_u32 s81, s79, 0
	s_add_u32 s82, s78, 0x400
	s_addc_u32 s83, s79, 0
	s_add_u32 s24, s80, 0x400
	s_addc_u32 s25, s81, 0
	s_mov_b32 m0, s26
	s_nop 0
	global_load_lds_dwordx4 v172, s[78:79]
	s_add_i32 m0, s26, 0x400
	s_nop 0
	global_load_lds_dwordx4 v172, s[80:81]
	s_add_i32 m0, s26, 0x2000
	s_nop 0
	global_load_lds_dwordx4 v172, s[82:83]
	s_add_i32 m0, s26, 0x2400
	s_nop 0
	global_load_lds_dwordx4 v172, s[24:25]
	v_readfirstlane_b32 s33, v177
	s_nop 3
	s_mov_b32 m0, s33
	s_nop 0
	global_load_lds_dwordx4 v176, s[78:79]
	s_add_u32 s6, s78, 0x3400
	s_addc_u32 s7, s79, 0
	s_add_i32 m0, s33, 0x400
	s_nop 0
	global_load_lds_dwordx4 v176, s[6:7]
	s_add_i32 m0, s33, 0x800
	s_nop 0
	global_load_lds_dwordx4 v176, s[80:81]
	s_add_u32 s6, s80, 0x3400
	s_addc_u32 s7, s81, 0
	s_add_i32 m0, s33, 0xc00
	s_nop 0
	global_load_lds_dwordx4 v176, s[6:7]

; __device__ __forceinline__ void gla_scan_phase2(LAS unsigned char* lds, const bf16_t* proj, const float* gbuf, const float* wgu  , const float* bg  ,
;                                                 bf16_t* ob0, bf16_t* ob1) {
;     ...
;                     const f32x4 ga = gna, gb = gnb;
;                     const unsigned srow = (unsigned)tok0 * (unsigned)(GINP * 2);
;                     unsigned short qv[16], kv[16];
; #pragma unroll
;                     for (int ii = 0; ii < 16; ++ii) { qv[ii] = __builtin_amdgcn_raw_buffer_load_b16(prs, qvoff, srow + (unsigned)(ii * GINP * 2), 0);
;                                                        kv[ii] = __builtin_amdgcn_raw_buffer_load_b16(prs, qvoff + 1024u, srow + (unsigned)(ii * GINP * 2), 0); }
;                     unsigned vw[16];
; #pragma unroll
;                     for (int ii = 0; ii < 16; ++ii) vw[ii] = __builtin_amdgcn_raw_buffer_load_b32(prs, vvoff, srow + (unsigned)(ii * GINP * 2), 0);
;                     { const int n1 = n + 1 < NCH ? n + 1 : n; const float* grow = gbuf + (size_t)(b * SEQ + (dir ? NCH - 1 - n1 : n1) * CH + r) * 32 + dir * 16 + 8 * hh;
;                       gna = *(const f32x4*)grow; gnb = *(const f32x4*)(grow + 4); }
;                     {
;                         u32x4 ah, al;
;                         ah.x = pk2(ga[0], ga[1]); ah.y = pk2(ga[2], ga[3]); ah.z = pk2(gb[0], gb[1]); ah.w = pk2(gb[2], gb[3]);
;                         al.x = pk2(ga[0] - bflo(ah.x), ga[1] - bfhi(ah.x)); al.y = pk2(ga[2] - bflo(ah.y), ga[3] - bfhi(ah.y));
;                         al.z = pk2(gb[0] - bflo(ah.z), gb[1] - bfhi(ah.z)); al.w = pk2(gb[2] - bflo(ah.w), gb[3] - bfhi(ah.w));
;                         const bf16x8 gah = __builtin_bit_cast(bf16x8, ah), gal = __builtin_bit_cast(bf16x8, al);
;                         f32x16 zacc;
; #pragma unroll
;                         for (int i = 0; i < 16; ++i) zacc[i] = zbias;
;                         zacc = MFMA32(gah, wbh, zacc); zacc = MFMA32(gal, wbh, zacc); zacc = MFMA32(gah, wbl, zacc);
; #pragma unroll
;                         for (int i = 0; i < 16; ++i) *(LAS float*)(lds + G2_Z + (((i & 3) + 8 * (i >> 2) + 4 * hh) * 128 + 32 * zd + r) * 4) = zacc[i];
;                     }
;                     G2_BAR();
;                     float cs[16];
; #pragma unroll
;                     for (int ii = 0; ii < 16; ++ii) {
.LBB0_220:
	s_waitcnt vmcnt(8)
	v_cvt_pk_bf16_f32 v102, v44, v45
	v_lshlrev_b32_e32 v16, 16, v102
	v_and_b32_e32 v17, 0xffff0000, v102
	v_cvt_pk_bf16_f32 v103, v46, v47
	v_cvt_pk_bf16_f32 v104, v40, v41
	v_cvt_pk_bf16_f32 v105, v42, v43
	v_pk_add_f32 v[16:17], v[44:45], v[16:17] neg_lo:[0,1] neg_hi:[0,1]
	s_and_b64 s[6:7], s[48:49], exec
	v_cvt_pk_bf16_f32 v44, v16, v17
	v_lshlrev_b32_e32 v16, 16, v103
	v_and_b32_e32 v17, 0xffff0000, v103
	v_pk_add_f32 v[16:17], v[46:47], v[16:17] neg_lo:[0,1] neg_hi:[0,1]
	s_cselect_b32 s0, s20, s8
	v_cvt_pk_bf16_f32 v45, v16, v17
	v_lshlrev_b32_e32 v16, 16, v104
	v_and_b32_e32 v17, 0xffff0000, v104
	v_pk_add_f32 v[16:17], v[40:41], v[16:17] neg_lo:[0,1] neg_hi:[0,1]
	v_lshlrev_b32_e32 v40, 16, v105
	v_cvt_pk_bf16_f32 v46, v16, v17
	v_mfma_f32_32x32x16_bf16 v[16:31], v[102:105], v[32:35], v[0:15]
	v_and_b32_e32 v41, 0xffff0000, v105
	v_add_f32_e64 v40, v42, -v40
	v_add_f32_e64 v41, v43, -v41
	s_lshl_b32 s0, s0, 5
	v_cvt_pk_bf16_f32 v47, v40, v41
	s_add_i32 s0, s0, s9
	s_mulk_i32 s0, 0x1a00
	s_or_b32 s6, s0, 0x1a00
	v_mfma_f32_32x32x16_bf16 v[16:31], v[44:47], v[32:35], v[16:31]
	s_or_b32 s7, s0, 0x3400
	s_add_i32 s15, s0, 0x4e00
	s_add_i32 s21, s0, 0x6800
	s_add_i32 s24, s0, 0x8200
	s_add_i32 s25, s0, 0x9c00
	s_add_i32 s26, s0, 0xb600
	s_add_i32 s28, s0, 0xd000
	s_add_i32 s33, s0, 0xea00
	s_add_i32 s78, s0, 0x10400
	s_add_i32 s79, s0, 0x11e00
	s_add_i32 s80, s0, 0x13800
	s_add_i32 s81, s0, 0x15200
	s_add_i32 s82, s0, 0x16c00
	s_add_i32 s83, s0, 0x18600
	s_cmp_lt_u32 s20, 63
	s_cselect_b64 s[6:7], -1, 0
	s_cmp_lg_u64 s[6:7], 0
	s_addc_u32 s0, s20, 0
	s_cmp_lg_u64 s[6:7], 0
	s_subb_u32 s6, 0, 0
	v_mfma_f32_32x32x16_bf16 v[16:31], v[102:105], v[36:39], v[16:31]
	s_add_i32 s15, s8, s6
	s_and_b64 s[6:7], s[48:49], exec
	s_cselect_b32 s0, s0, s15
	v_lshl_add_u32 v40, s0, 5, v52
	v_ashrrev_i32_e32 v41, 31, v40
	v_lshlrev_b64 v[40:41], 7, v[40:41]
	v_lshl_add_u64 v[44:45], v[48:49], 0, v[40:41]
	global_load_dwordx4 v[40:43], v[44:45], off offset:16
	s_nop 0
	global_load_dwordx4 v[44:47], v[44:45], off
	s_nop 1
	ds_write_b32 v214, v16
	ds_write_b32 v215, v17
	ds_write_b32 v216, v18
	ds_write_b32 v217, v19
	ds_write_b32 v218, v20
	ds_write_b32 v219, v21
	ds_write_b32 v220, v22
	ds_write_b32 v221, v23
	ds_write_b32 v222, v24
	ds_write_b32 v223, v25
	ds_write_b32 v224, v26
	ds_write_b32 v225, v27
	ds_write_b32 v226, v28
	ds_write_b32 v227, v29
	ds_write_b32 v228, v30
	ds_write_b32 v229, v31
	s_waitcnt lgkmcnt(0)
	s_barrier
	ds_read2st64_b32 v[118:119], v230 offset1:2
	ds_read2st64_b32 v[120:121], v230 offset0:4 offset1:6
	ds_read2st64_b32 v[122:123], v230 offset0:8 offset1:10
	ds_read2st64_b32 v[124:125], v230 offset0:12 offset1:14
	ds_read2st64_b32 v[126:127], v230 offset0:16 offset1:18
	ds_read2st64_b32 v[128:129], v230 offset0:20 offset1:22
	ds_read2st64_b32 v[130:131], v230 offset0:24 offset1:26
	ds_read2st64_b32 v[132:133], v230 offset0:28 offset1:30
	s_andn2_b64 vcc, exec, s[68:69]
	s_mov_b64 s[6:7], -1
	s_waitcnt lgkmcnt(4)
	v_mul_f32_e64 v134, |v118|, s1
	v_mul_f32_e64 v135, |v119|, s1
	v_mul_f32_e64 v136, |v120|, s1
	v_mul_f32_e64 v137, |v121|, s1
	v_mul_f32_e64 v138, |v122|, s1
	v_mul_f32_e64 v139, |v123|, s1
	v_mul_f32_e64 v140, |v124|, s1
	v_mul_f32_e64 v141, |v125|, s1
	s_waitcnt lgkmcnt(0)
	v_mul_f32_e64 v142, |v126|, s1
	v_mul_f32_e64 v143, |v127|, s1
	v_mul_f32_e64 v144, |v128|, s1
	v_mul_f32_e64 v145, |v129|, s1
	v_mul_f32_e64 v146, |v130|, s1
	v_mul_f32_e64 v147, |v131|, s1
	v_mul_f32_e64 v148, |v132|, s1
	v_mul_f32_e64 v149, |v133|, s1
	v_exp_f32_e32 v134, v134
	v_exp_f32_e32 v135, v135
	v_exp_f32_e32 v136, v136
	v_exp_f32_e32 v137, v137
	v_exp_f32_e32 v138, v138
	v_exp_f32_e32 v139, v139
	v_exp_f32_e32 v140, v140
	v_exp_f32_e32 v141, v141
	v_exp_f32_e32 v142, v142
	v_exp_f32_e32 v143, v143
	v_exp_f32_e32 v144, v144
	v_exp_f32_e32 v145, v145
	v_exp_f32_e32 v146, v146
	v_exp_f32_e32 v147, v147
	v_exp_f32_e32 v148, v148
	v_exp_f32_e32 v149, v149
	v_min_f32_e32 v118, 0, v118
	v_min_f32_e32 v119, 0, v119
	v_min_f32_e32 v120, 0, v120
	v_min_f32_e32 v121, 0, v121
	v_min_f32_e32 v122, 0, v122
	v_min_f32_e32 v123, 0, v123
	v_min_f32_e32 v124, 0, v124
	v_min_f32_e32 v125, 0, v125
	v_min_f32_e32 v126, 0, v126
	v_min_f32_e32 v127, 0, v127
	v_min_f32_e32 v128, 0, v128
	v_min_f32_e32 v129, 0, v129
	v_min_f32_e32 v130, 0, v130
	v_min_f32_e32 v131, 0, v131
	v_min_f32_e32 v132, 0, v132
	v_min_f32_e32 v133, 0, v133
	v_add_f32_e32 v134, 1.0, v134
	v_add_f32_e32 v135, 1.0, v135
	v_add_f32_e32 v136, 1.0, v136
	v_add_f32_e32 v137, 1.0, v137
	v_add_f32_e32 v138, 1.0, v138
	v_add_f32_e32 v139, 1.0, v139
	v_add_f32_e32 v140, 1.0, v140
	v_add_f32_e32 v141, 1.0, v141
	v_add_f32_e32 v142, 1.0, v142
	v_add_f32_e32 v143, 1.0, v143
	v_add_f32_e32 v144, 1.0, v144
	v_add_f32_e32 v145, 1.0, v145
	v_add_f32_e32 v146, 1.0, v146
	v_add_f32_e32 v147, 1.0, v147
	v_add_f32_e32 v148, 1.0, v148
	v_add_f32_e32 v149, 1.0, v149
	v_log_f32_e32 v134, v134
	v_log_f32_e32 v135, v135
	v_log_f32_e32 v136, v136
	v_log_f32_e32 v137, v137
	v_log_f32_e32 v138, v138
	v_log_f32_e32 v139, v139
	v_log_f32_e32 v140, v140
	v_log_f32_e32 v141, v141
	v_log_f32_e32 v142, v142
	v_log_f32_e32 v143, v143
	v_log_f32_e32 v144, v144
	v_log_f32_e32 v145, v145
	v_log_f32_e32 v146, v146
	v_log_f32_e32 v147, v147
	v_log_f32_e32 v148, v148
	v_log_f32_e32 v149, v149
	v_mul_f32_e32 v134, 0x3d800000, v134
	v_mul_f32_e32 v135, 0x3d800000, v135
	v_mul_f32_e32 v136, 0x3d800000, v136
	v_mul_f32_e32 v137, 0x3d800000, v137
	v_mul_f32_e32 v138, 0x3d800000, v138
	v_mul_f32_e32 v139, 0x3d800000, v139
	v_mul_f32_e32 v140, 0x3d800000, v140
	v_mul_f32_e32 v141, 0x3d800000, v141
	v_mul_f32_e32 v142, 0x3d800000, v142
	v_mul_f32_e32 v143, 0x3d800000, v143
	v_mul_f32_e32 v144, 0x3d800000, v144
	v_mul_f32_e32 v145, 0x3d800000, v145
	v_mul_f32_e32 v146, 0x3d800000, v146
	v_mul_f32_e32 v147, 0x3d800000, v147
	v_mul_f32_e32 v148, 0x3d800000, v148
	v_mul_f32_e32 v149, 0x3d800000, v149
	v_fma_f32 v16, v118, s10, -v134
	v_fma_f32 v25, v119, s10, -v135
	v_fma_f32 v26, v120, s10, -v136
	v_fma_f32 v29, v121, s10, -v137
	v_fma_f32 v30, v122, s10, -v138
	v_fma_f32 v102, v123, s10, -v139
	v_fma_f32 v104, v124, s10, -v140
	v_fma_f32 v105, v125, s10, -v141
	v_fma_f32 v108, v126, s10, -v142
	v_fma_f32 v109, v127, s10, -v143
	v_fma_f32 v111, v128, s10, -v144
	v_fma_f32 v112, v129, s10, -v145
	v_fma_f32 v113, v130, s10, -v146
	v_fma_f32 v114, v131, s10, -v147
	v_fma_f32 v116, v132, s10, -v148
	v_fma_f32 v17, v133, s10, -v149
	s_cbranch_vccnz .LBB0_222
	v_add_f32_e32 v18, v116, v17
	v_add_f32_e32 v19, v114, v18
	v_add_f32_e32 v20, v113, v19
	v_add_f32_e32 v21, v112, v20
	v_add_f32_e32 v22, v111, v21
	v_add_f32_e32 v23, v109, v22
	v_add_f32_e32 v24, v108, v23
	v_add_f32_e32 v27, v105, v24
	v_add_f32_e32 v28, v104, v27
	v_add_f32_e32 v31, v102, v28
	v_add_f32_e32 v103, v30, v31
	v_add_f32_e32 v106, v29, v103
	v_add_f32_e32 v107, v26, v106
	v_add_f32_e32 v110, v25, v107
	v_add_f32_e32 v115, v16, v110
	s_mov_b64 s[6:7], 0

; #define LAS __attribute__((address_space(3)))
; __device__ __forceinline__ float bf2f(unsigned u16) { return __uint_as_float(u16 << 16); }
; #define G2_BAR() do { asm volatile("s_waitcnt lgkmcnt(0)" ::: "memory"); __builtin_amdgcn_s_barrier(); asm volatile("" ::: "memory"); } while (0)
; __device__ __forceinline__ void gla_scan_phase2(LAS unsigned char* lds, const bf16_t* proj, const float* gbuf, const float* wgu  , const float* bg  ,
;                                                 bf16_t* ob0, bf16_t* ob1) {
;     ...
;                     G2_BAR();
;                     {
;                         const float t0 = *(const LAS float*)(lds + G2_SEG + d * 4), t1 = *(const LAS float*)(lds + G2_SEG + (128 + d) * 4);
;                         const float prefix = dir == 0 ? (seg ? t0 : 0.f) : (seg ? 0.f : t1);
;                         const float ebl = __builtin_amdgcn_exp2f(t0 + t1);
;                         unsigned kd[8];
; #pragma unroll
;                         for (int ii = 0; ii < 16; ii += 2) {
;                             const float e0 = __builtin_amdgcn_exp2f(prefix + cs[ii]), e1 = __builtin_amdgcn_exp2f(prefix + cs[ii + 1]);
;                             const float q0 = bf2f(qv[ii]), q1 = bf2f(qv[ii + 1]);
;                             const float k0 = bf2f(kv[ii]) * __builtin_amdgcn_rcpf(e0), k1 = bf2f(kv[ii + 1]) * __builtin_amdgcn_rcpf(e1);
.LBB0_225:
	s_waitcnt vmcnt(2)
	ds_write_b32 v231, v115
	s_waitcnt lgkmcnt(0)
	s_barrier
	v_add_u32_e32 v25, s11, v202
	ds_read2st64_b32 v[104:105], v25 offset1:2
	ds_read_u16 v98, v173
	ds_read_u16 v100, v173 offset:256
	ds_read_u16 v94, v173 offset:512
	ds_read_u16 v96, v173 offset:768
	ds_read_u16 v90, v173 offset:1024
	ds_read_u16 v92, v173 offset:1280
	ds_read_u16 v82, v173 offset:1536
	ds_read_u16 v84, v173 offset:1792
	ds_read_u16 v99, v173 offset:8192
	ds_read_u16 v101, v173 offset:8448
	ds_read_u16 v95, v173 offset:8704
	ds_read_u16 v97, v173 offset:8960
	ds_read_u16 v91, v173 offset:9216
	ds_read_u16 v93, v173 offset:9472
	ds_read_u16 v83, v173 offset:9728
	ds_read_u16 v85, v173 offset:9984
	ds_read_u16 v86, v173 offset:2048
	ds_read_u16 v88, v173 offset:2304
	ds_read_u16 v78, v173 offset:2560
	ds_read_u16 v80, v173 offset:2816
	ds_read_u16 v74, v173 offset:3072
	ds_read_u16 v76, v173 offset:3328
	ds_read_u16 v70, v173 offset:3584
	ds_read_u16 v72, v173 offset:3840
	ds_read_u16 v87, v173 offset:10240
	ds_read_u16 v89, v173 offset:10496
	ds_read_u16 v79, v173 offset:10752
	ds_read_u16 v81, v173 offset:11008
	ds_read_u16 v75, v173 offset:11264
	ds_read_u16 v77, v173 offset:11520
	ds_read_u16 v71, v173 offset:11776
	ds_read_u16 v73, v173 offset:12032
	ds_read_b32 v68, v170
	ds_read_b32 v69, v170 offset:512
	ds_read_b32 v66, v170 offset:1024
	ds_read_b32 v67, v170 offset:1536
	ds_read_b32 v64, v170 offset:2048
	ds_read_b32 v65, v170 offset:2560
	ds_read_b32 v62, v170 offset:3072
	ds_read_b32 v63, v170 offset:3584
	ds_read_b32 v60, v170 offset:4096
	ds_read_b32 v61, v170 offset:4608
	ds_read_b32 v58, v170 offset:5120
	ds_read_b32 v59, v170 offset:5632
	ds_read_b32 v56, v170 offset:6144
	ds_read_b32 v57, v170 offset:6656
	ds_read_b32 v54, v170 offset:7168
	ds_read_b32 v55, v170 offset:7680
	s_bitcmp1_b32 s20, 0
	s_cselect_b32 s0, 0xa800, 0
	s_waitcnt lgkmcnt(0)
	v_lshlrev_b32_e32 v111, 16, v100
	s_add_i32 s15, s0, 0
	s_waitcnt lgkmcnt(0)
; #define LAS __attribute__((address_space(3)))
; __device__ __forceinline__ unsigned pk2(float lo, float hi) { f32x2 v = {lo, hi}; bf16x2_t b = __builtin_convertvector(v, bf16x2_t); return __builtin_bit_cast(unsigned, b); }
; __device__ __forceinline__ void gla_scan_phase2(LAS unsigned char* lds, const bf16_t* proj, const float* gbuf, const float* wgu  , const float* bg  ,
;                                                 bf16_t* ob0, bf16_t* ob1) {
;     ...
;                         const float t0 = *(const LAS float*)(lds + G2_SEG + d * 4), t1 = *(const LAS float*)(lds + G2_SEG + (128 + d) * 4);
;                         const float prefix = dir == 0 ? (seg ? t0 : 0.f) : (seg ? 0.f : t1);
;                         const float ebl = __builtin_amdgcn_exp2f(t0 + t1);
;                         unsigned kd[8];
; #pragma unroll
;                         for (int ii = 0; ii < 16; ii += 2) {
;                             const float e0 = __builtin_amdgcn_exp2f(prefix + cs[ii]), e1 = __builtin_amdgcn_exp2f(prefix + cs[ii + 1]);
;                             const float q0 = bf2f(qv[ii]), q1 = bf2f(qv[ii + 1]);
;                             const float k0 = bf2f(kv[ii]) * __builtin_amdgcn_rcpf(e0), k1 = bf2f(kv[ii + 1]) * __builtin_amdgcn_rcpf(e1);
;                             const unsigned qd = pk2(q0 * e0, q1 * e1);
;                             const unsigned ki = pk2(k0, k1);
;                             kd[ii >> 1] = pk2(k0 * ebl, k1 * ebl);
;                             const int i0 = 16 * seg + ii;
;                             *(LAS unsigned short*)(set + G2_QD + i0 * 272 + d * 2) = (unsigned short)(qd & 0xffffu);
;                             *(LAS unsigned short*)(set + G2_QD + (i0 + 1) * 272 + d * 2) = (unsigned short)(qd >> 16);
;                             *(LAS unsigned short*)(lds + G2_KI + i0 * 272 + d * 2) = (unsigned short)(ki & 0xffffu);
;                             *(LAS unsigned short*)(lds + G2_KI + (i0 + 1) * 272 + d * 2) = (unsigned short)(ki >> 16);
;                         }
;                         *(LAS u32x4*)(set + G2_KDT + d * 80 + seg * 32) = (u32x4){kd[0], kd[1], kd[2], kd[3]};
;                         *(LAS u32x4*)(set + G2_KDT + d * 80 + seg * 32 + 16) = (u32x4){kd[4], kd[5], kd[6], kd[7]};
;                         if (seg == 0) *(LAS float*)(set + G2_EBL + d * 4) = ebl;
	v_cndmask_b32_e64 v25, v104, 0, s[38:39]
	v_cndmask_b32_e64 v26, 0, v105, s[38:39]
	v_cndmask_b32_e64 v102, v26, v25, s[48:49]
	v_add_f32_e32 v16, v16, v102
	v_exp_f32_e32 v108, v16
	v_add_f32_e32 v16, v110, v102
	v_exp_f32_e32 v109, v16
	v_add_f32_e32 v16, v104, v105
	v_rcp_f32_e32 v104, v108
	v_lshlrev_b32_e32 v110, 16, v98
	v_rcp_f32_e32 v105, v109
	v_pk_mul_f32 v[108:109], v[108:109], v[110:111]
	s_nop 0
	v_lshlrev_b32_e32 v101, 16, v101
	v_cvt_pk_bf16_f32 v25, v108, v109
	v_add3_u32 v108, s15, v201, v211
	v_lshlrev_b32_e32 v100, 16, v99
	ds_write_b16 v108, v25
	ds_write_b16_d16_hi v108, v25 offset:272
	v_add_f32_e32 v25, v107, v102
	v_pk_mul_f32 v[98:99], v[104:105], v[100:101]
	v_exp_f32_e32 v100, v25
	v_add_f32_e32 v25, v106, v102
	v_exp_f32_e32 v101, v25
	v_lshlrev_b32_e32 v107, 16, v96
	v_lshlrev_b32_e32 v106, 16, v94
	v_rcp_f32_e32 v104, v100
	v_rcp_f32_e32 v105, v101
	v_pk_mul_f32 v[100:101], v[100:101], v[106:107]
	v_cvt_pk_bf16_f32 v26, v98, v99
	v_cvt_pk_bf16_f32 v25, v100, v101
	ds_write_b16 v232, v26
	ds_write_b16_d16_hi v232, v26 offset:272
	ds_write_b16 v108, v25 offset:544
	ds_write_b16_d16_hi v108, v25 offset:816
	v_add_f32_e32 v25, v103, v102
	v_exp_f32_e32 v16, v16
	v_exp_f32_e32 v30, v25
	v_add_f32_e32 v25, v31, v102
	v_exp_f32_e32 v31, v25
	s_nop 0
	v_lshlrev_b32_e32 v97, 16, v97
	v_lshlrev_b32_e32 v96, 16, v95
	v_pk_mul_f32 v[94:95], v[104:105], v[96:97]
	v_pk_mul_f32 v[98:99], v[16:17], v[98:99] op_sel_hi:[0,1]
	v_cvt_pk_bf16_f32 v26, v94, v95
	v_pk_mul_f32 v[94:95], v[16:17], v[94:95] op_sel_hi:[0,1]
	v_lshlrev_b32_e32 v97, 16, v92
	v_lshlrev_b32_e32 v96, 16, v90
	v_cvt_pk_bf16_f32 v98, v98, v99
	v_cvt_pk_bf16_f32 v99, v94, v95
	v_rcp_f32_e32 v94, v30
	v_rcp_f32_e32 v95, v31
	v_pk_mul_f32 v[30:31], v[30:31], v[96:97]
	ds_write_b16 v232, v26 offset:544
	ds_write_b16_d16_hi v232, v26 offset:816
	v_cvt_pk_bf16_f32 v25, v30, v31
	ds_write_b16 v108, v25 offset:1088
	ds_write_b16_d16_hi v108, v25 offset:1360
	v_add_f32_e32 v25, v28, v102
	v_exp_f32_e32 v26, v25
	v_add_f32_e32 v25, v27, v102
	v_exp_f32_e32 v27, v25
	s_nop 0
	v_lshlrev_b32_e32 v31, 16, v93
	v_lshlrev_b32_e32 v30, 16, v91
	v_pk_mul_f32 v[30:31], v[94:95], v[30:31]
	v_rcp_f32_e32 v28, v26
	v_cvt_pk_bf16_f32 v29, v30, v31
	v_pk_mul_f32 v[30:31], v[16:17], v[30:31] op_sel_hi:[0,1]
	v_cvt_pk_bf16_f32 v100, v30, v31
	ds_write_b16 v232, v29 offset:1088
	ds_write_b16_d16_hi v232, v29 offset:1360
	v_rcp_f32_e32 v29, v27
	v_lshlrev_b32_e32 v31, 16, v84
	v_lshlrev_b32_e32 v30, 16, v82
	v_pk_mul_f32 v[26:27], v[26:27], v[30:31]
	v_add_f32_e32 v24, v24, v102
	v_cvt_pk_bf16_f32 v25, v26, v27
	v_add_f32_e32 v23, v23, v102
	s_nop 0
	v_lshlrev_b32_e32 v27, 16, v85
	v_lshlrev_b32_e32 v26, 16, v83
	ds_write_b16 v108, v25 offset:1632
	ds_write_b16_d16_hi v108, v25 offset:1904
	v_exp_f32_e32 v24, v24
	v_exp_f32_e32 v25, v23
	v_pk_mul_f32 v[26:27], v[28:29], v[26:27]
	s_nop 0
	v_lshlrev_b32_e32 v29, 16, v88
	v_cvt_pk_bf16_f32 v28, v26, v27
	v_pk_mul_f32 v[26:27], v[16:17], v[26:27] op_sel_hi:[0,1]
	ds_write_b16 v232, v28 offset:1632
	ds_write_b16_d16_hi v232, v28 offset:1904
	v_lshlrev_b32_e32 v28, 16, v86
	v_cvt_pk_bf16_f32 v101, v26, v27
	v_rcp_f32_e32 v26, v24
	v_rcp_f32_e32 v27, v25
	v_pk_mul_f32 v[24:25], v[24:25], v[28:29]
	v_add_f32_e32 v22, v22, v102
	v_cvt_pk_bf16_f32 v23, v24, v25
	v_add_f32_e32 v21, v21, v102
	ds_write_b16 v108, v23 offset:2176
	ds_write_b16_d16_hi v108, v23 offset:2448
	v_exp_f32_e32 v22, v22
	v_exp_f32_e32 v23, v21
	s_nop 0
	v_lshlrev_b32_e32 v25, 16, v89
	v_lshlrev_b32_e32 v24, 16, v87
	v_pk_mul_f32 v[24:25], v[26:27], v[24:25]
	v_lshlrev_b32_e32 v29, 16, v80
	v_cvt_pk_bf16_f32 v26, v24, v25
	v_lshlrev_b32_e32 v28, 16, v78
	ds_write_b16 v232, v26 offset:2176
	ds_write_b16_d16_hi v232, v26 offset:2448
	v_rcp_f32_e32 v26, v22
	v_rcp_f32_e32 v27, v23
	v_pk_mul_f32 v[22:23], v[22:23], v[28:29]
	v_add_f32_e32 v20, v20, v102
	v_cvt_pk_bf16_f32 v21, v22, v23
	v_add_f32_e32 v19, v19, v102
	ds_write_b16 v108, v21 offset:2720
	ds_write_b16_d16_hi v108, v21 offset:2992
	v_exp_f32_e32 v20, v20
	v_exp_f32_e32 v21, v19
	s_nop 0
	v_lshlrev_b32_e32 v23, 16, v81
	v_lshlrev_b32_e32 v22, 16, v79
	v_pk_mul_f32 v[22:23], v[26:27], v[22:23]
	v_pk_mul_f32 v[24:25], v[16:17], v[24:25] op_sel_hi:[0,1]
	v_cvt_pk_bf16_f32 v26, v22, v23
	v_pk_mul_f32 v[22:23], v[16:17], v[22:23] op_sel_hi:[0,1]
	v_cvt_pk_bf16_f32 v24, v24, v25
	v_cvt_pk_bf16_f32 v25, v22, v23
	v_rcp_f32_e32 v22, v20
	v_rcp_f32_e32 v23, v21
	ds_write_b16 v232, v26 offset:2720
	ds_write_b16_d16_hi v232, v26 offset:2992
	v_lshlrev_b32_e32 v27, 16, v76
	v_lshlrev_b32_e32 v26, 16, v74
	v_pk_mul_f32 v[20:21], v[20:21], v[26:27]
	v_add_f32_e32 v18, v18, v102
	v_cvt_pk_bf16_f32 v19, v20, v21
	s_nop 0
	v_lshlrev_b32_e32 v21, 16, v77
	v_lshlrev_b32_e32 v20, 16, v75
	v_pk_mul_f32 v[20:21], v[22:23], v[20:21]
	ds_write_b16 v108, v19 offset:3264
	ds_write_b16_d16_hi v108, v19 offset:3536
	v_cvt_pk_bf16_f32 v22, v20, v21
	v_pk_mul_f32 v[20:21], v[16:17], v[20:21] op_sel_hi:[0,1]
	v_add_f32_e32 v17, v17, v102
	v_exp_f32_e32 v18, v18
	v_exp_f32_e32 v19, v17
	v_cvt_pk_bf16_f32 v26, v20, v21
	ds_write_b16 v232, v22 offset:3264
	ds_write_b16_d16_hi v232, v22 offset:3536
	v_rcp_f32_e32 v20, v18
	v_rcp_f32_e32 v21, v19
	v_lshlrev_b32_e32 v23, 16, v72
	v_lshlrev_b32_e32 v22, 16, v70
	v_pk_mul_f32 v[18:19], v[18:19], v[22:23]
	s_nop 0
	v_cvt_pk_bf16_f32 v17, v18, v19
	s_nop 0
	v_lshlrev_b32_e32 v19, 16, v73
	v_lshlrev_b32_e32 v18, 16, v71
	v_pk_mul_f32 v[18:19], v[20:21], v[18:19]
	s_nop 0
	v_cvt_pk_bf16_f32 v20, v18, v19
	v_pk_mul_f32 v[18:19], v[16:17], v[18:19] op_sel_hi:[0,1]
	ds_write_b16 v108, v17 offset:3808
	ds_write_b16_d16_hi v108, v17 offset:4080
	ds_write_b16 v232, v20 offset:3808
	ds_write_b16_d16_hi v232, v20 offset:4080
	v_add3_u32 v17, s15, v203, v204
	v_cvt_pk_bf16_f32 v27, v18, v19
	ds_write_b128 v17, v[98:101] offset:8704
	ds_write_b128 v17, v[24:27] offset:8720
	s_and_saveexec_b64 s[6:7], s[38:39]
	s_cbranch_execz .LBB0_219
	v_add_u32_e32 v17, s15, v202
	ds_write_b32 v17, v16 offset:41984
	s_branch .LBB0_219

; #define LAS __attribute__((address_space(3)))
; __global__ void __launch_bounds__(NTHREADS, 2) fwd_megakernel(Params p) {
;     extern __shared__ __attribute__((aligned(16))) unsigned char lds_raw[];
;     LAS unsigned char* lds = (LAS unsigned char*)lds_raw;
	.amdhsa_kernel _Z14fwd_megakernel6Params
		.amdhsa_group_segment_fixed_size 8192
		.amdhsa_private_segment_fixed_size 0
		.amdhsa_kernarg_size 384
		.amdhsa_user_sgpr_count 2
		.amdhsa_user_sgpr_dispatch_ptr 0
		.amdhsa_user_sgpr_queue_ptr 0
		.amdhsa_user_sgpr_kernarg_segment_ptr 1
		.amdhsa_user_sgpr_dispatch_id 0
		.amdhsa_user_sgpr_kernarg_preload_length 0
		.amdhsa_user_sgpr_kernarg_preload_offset 0
		.amdhsa_user_sgpr_private_segment_size 0
		.amdhsa_uses_dynamic_stack 0
		.amdhsa_enable_private_segment 0
		.amdhsa_system_sgpr_workgroup_id_x 1
		.amdhsa_system_sgpr_workgroup_id_y 0
		.amdhsa_system_sgpr_workgroup_id_z 0
		.amdhsa_system_sgpr_workgroup_info 0
		.amdhsa_system_vgpr_workitem_id 2
		.amdhsa_next_free_vgpr 254
		.amdhsa_next_free_sgpr 100
		.amdhsa_accum_offset 256
		.amdhsa_reserve_vcc 1
		.amdhsa_float_round_mode_32 0
		.amdhsa_float_round_mode_16_64 0
		.amdhsa_float_denorm_mode_32 3
		.amdhsa_float_denorm_mode_16_64 3
		.amdhsa_dx10_clamp 1
		.amdhsa_ieee_mode 1
		.amdhsa_fp16_overflow 0
		.amdhsa_tg_split 0
		.amdhsa_exception_fp_ieee_invalid_op 0
		.amdhsa_exception_fp_denorm_src 0
		.amdhsa_exception_fp_ieee_div_zero 0
		.amdhsa_exception_fp_ieee_overflow 0
		.amdhsa_exception_fp_ieee_underflow 0
		.amdhsa_exception_fp_ieee_inexact 0
		.amdhsa_exception_int_div_zero 0
	.end_amdhsa_kernel

; #define LAS __attribute__((address_space(3)))
; __global__ void __launch_bounds__(NTHREADS, 2) fwd_megakernel(Params p) {
;     extern __shared__ __attribute__((aligned(16))) unsigned char lds_raw[];
;     LAS unsigned char* lds = (LAS unsigned char*)lds_raw;
amdhsa.kernels:
  - .agpr_count:     0
    .args:
      - .offset:         0
        .size:           128
        .value_kind:     by_value
      - .offset:         128
        .size:           4
        .value_kind:     hidden_block_count_x
      - .offset:         132
        .size:           4
        .value_kind:     hidden_block_count_y
      - .offset:         136
        .size:           4
        .value_kind:     hidden_block_count_z
      - .offset:         140
        .size:           2
        .value_kind:     hidden_group_size_x
      - .offset:         142
        .size:           2
        .value_kind:     hidden_group_size_y
      - .offset:         144
        .size:           2
        .value_kind:     hidden_group_size_z
      - .offset:         146
        .size:           2
        .value_kind:     hidden_remainder_x
      - .offset:         148
        .size:           2
        .value_kind:     hidden_remainder_y
      - .offset:         150
        .size:           2
        .value_kind:     hidden_remainder_z
      - .offset:         168
        .size:           8
        .value_kind:     hidden_global_offset_x
      - .offset:         176
        .size:           8
        .value_kind:     hidden_global_offset_y
      - .offset:         184
        .size:           8
        .value_kind:     hidden_global_offset_z
      - .offset:         192
        .size:           2
        .value_kind:     hidden_grid_dims
      - .offset:         216
        .size:           8
        .value_kind:     hidden_multigrid_sync_arg
      - .offset:         248
        .size:           4
        .value_kind:     hidden_dynamic_lds_size
    .group_segment_fixed_size: 8192
    .kernarg_segment_align: 8
    .kernarg_segment_size: 384
    .language:       OpenCL C
    .language_version:
      - 2
      - 0
    .max_flat_workgroup_size: 512
    .name:           _Z14fwd_megakernel6Params
    .private_segment_fixed_size: 0
    .sgpr_count:     106
    .sgpr_spill_count: 146
    .symbol:         _Z14fwd_megakernel6Params.kd
    .uniform_work_group_size: 1
    .uses_dynamic_stack: false
    .vgpr_count:     254
    .vgpr_spill_count: 0
    .wavefront_size: 64
